# accumulator zeroing before each K-loop with 64-bit moves of inline 0 (64 instead of 127 VALU per tile), on top of best K-loop version
# baseline (speedup 1.0000x reference)
; #define LAS __attribute__((address_space(3)))
; #define PG8_STAGE(bufoff, gbase, voff) do { _Pragma("unroll") for (int _i = 0; _i < 2; ++_i) \
;         __builtin_amdgcn_global_load_lds((const unsigned*)((const char*)(gbase) + (voff)[_i]), (LAS unsigned*)(lds + (bufoff) + ldsw + _i * 8192), 16, 0, 0); } while (0)
; #define PG8_WAIT_V(n) asm volatile("s_waitcnt vmcnt(" #n ")" ::: "memory")
; #define PG8_BAR __builtin_amdgcn_s_barrier()
; __device__ __forceinline__ void lnfold_prefetch(LAS float* vl, const float* stats, const float* gW, const float* bW, const Unit& u, int wr, int wc, int lane) {
;     LAS float* slot = vl + (wr * 4 + wc) * 512;
;     const int rowb = u.pm * BM + wr * 64 + (lane >> 5) * HALF + (lane & 31) * 2;
;     const int col = u.pn * BM + wc * 32 + (lane < 32 ? lane : 96 + lane);
;     __builtin_amdgcn_global_load_lds((const unsigned*)(stats + 2 * (size_t)rowb), (LAS unsigned*)slot, 16, 0, 0);
;     __builtin_amdgcn_global_load_lds((const unsigned*)(gW + col), (LAS unsigned*)(slot + 256), 4, 0, 0);
;     __builtin_amdgcn_global_load_lds((const unsigned*)(bW + col), (LAS unsigned*)(slot + 320), 4, 0, 0);
; template <class Epi>
; __device__ __forceinline__ void gemm_phase(LAS unsigned char* lds, const Gemm g0, const StaticOrder& S, const Epi& E) {
;     ...
;     f32x4 acc[2][2][4][2];
; #pragma unroll
;     for (int a = 0; a < 2; ++a)
; #pragma unroll
;         for (int b = 0; b < 2; ++b)
; #pragma unroll
;             for (int m = 0; m < 4; ++m)
; #pragma unroll
;                 for (int n = 0; n < 2; ++n) acc[a][b][m][n] = (f32x4){0.f, 0.f, 0.f, 0.f};
;     f16x8 At[4][2], B0[2][2], B1[2][2];
;     const char* cA = (const char*)g.A + (size_t)cur.pm * tstep; const char* cB = (const char*)g.Bt + (size_t)cur.pn * tstep;
;     PG8_STAGE(PG8_SB(0, 0), cB, voffB); PG8_STAGE(PG8_SA(0, 0), cA, voffA); PG8_STAGE(PG8_SB(0, 1), cB + hstep, voffB); PG8_STAGE(PG8_SA(0, 1), cA + hstep, voffA);
;     if (wr == 1) PG8_BAR;
;     PG8_WAIT_V(4); PG8_BAR;
;     PG8_STAGE(PG8_SB(1, 0), cB + kstep, voffB); PG8_STAGE(PG8_SA(1, 0), cA + kstep, voffA); PG8_STAGE(PG8_SB(1, 1), cB + hstep + kstep, voffB);
;     PG8_WAIT_V(6); PG8_BAR;
;     for (;;) {
;         const bool has_next = S.next(ui + 1, nxt);
;         const char* nA = has_next ? (const char*)g.A + (size_t)nxt.pm * tstep : cA; const char* nB = has_next ? (const char*)g.Bt + (size_t)nxt.pn * tstep : cB;
.LBB0_197:
	s_ashr_i32 s37, s36, 31
	v_mov_b64_e32 v[2:3], 0x300
	s_lshl_b64 s[24:25], s[36:37], 20
	v_cmp_lt_i64_e32 vcc, s[38:39], v[2:3]
	s_add_u32 s38, s8, s24
	s_addc_u32 s39, s9, s25
	s_and_b64 s[24:25], vcc, exec
	s_cselect_b32 s75, s39, s51
	s_cselect_b32 s80, s38, s50
	s_ashr_i32 s35, s34, 31
	s_lshl_b64 s[24:25], s[34:35], 20
	s_add_u32 s48, s10, s24
	s_addc_u32 s49, s11, s25
	s_and_b64 s[24:25], vcc, exec
	s_cselect_b32 s81, s49, s1
	s_cselect_b32 s82, s48, s0
	s_lshl_b32 s37, s22, 8
	s_lshl_b32 s35, s74, 8
	v_add_u32_e32 v2, s37, v215
	v_add_u32_e32 v4, s35, v216
	s_add_u32 s24, s0, 0x100
	v_ashrrev_i32_e32 v3, 31, v2
	v_ashrrev_i32_e32 v5, 31, v4
	s_addc_u32 s25, s1, 0
	v_lshlrev_b64 v[4:5], 2, v[4:5]
	v_lshl_add_u64 v[134:135], v[2:3], 3, s[14:15]
	s_add_u32 s0, s50, 0x80080
	v_mov_b32_e32 v2, 0
	v_lshl_add_u64 v[130:131], s[26:27], 0, v[4:5]
	v_lshl_add_u64 v[132:133], s[20:21], 0, v[4:5]
	s_addc_u32 s1, s51, 0
	s_mov_b32 s83, -2
	v_mov_b32_e32 v3, v2
	v_mov_b64_e32 v[4:5], 0
	v_mov_b64_e32 v[6:7], 0
	v_mov_b64_e32 v[8:9], 0
	v_mov_b64_e32 v[10:11], 0
	v_mov_b64_e32 v[12:13], 0
	v_mov_b64_e32 v[14:15], 0
	v_mov_b64_e32 v[16:17], 0
	v_mov_b64_e32 v[18:19], 0
	v_mov_b64_e32 v[20:21], 0
	v_mov_b64_e32 v[22:23], 0
	v_mov_b64_e32 v[24:25], 0
	v_mov_b64_e32 v[26:27], 0
	v_mov_b64_e32 v[28:29], 0
	v_mov_b64_e32 v[30:31], 0
	v_mov_b64_e32 v[32:33], 0
	v_mov_b64_e32 v[34:35], 0
	v_mov_b64_e32 v[36:37], 0
	v_mov_b64_e32 v[38:39], 0
	v_mov_b64_e32 v[40:41], 0
	v_mov_b64_e32 v[42:43], 0
	v_mov_b64_e32 v[44:45], 0
	v_mov_b64_e32 v[46:47], 0
	v_mov_b64_e32 v[48:49], 0
	v_mov_b64_e32 v[50:51], 0
	v_mov_b64_e32 v[52:53], 0
	v_mov_b64_e32 v[54:55], 0
	v_mov_b64_e32 v[56:57], 0
	v_mov_b64_e32 v[58:59], 0
	v_mov_b64_e32 v[60:61], 0
	v_mov_b64_e32 v[62:63], 0
	v_mov_b64_e32 v[64:65], 0
	v_mov_b64_e32 v[66:67], 0
	v_mov_b64_e32 v[68:69], 0
	v_mov_b64_e32 v[70:71], 0
	v_mov_b64_e32 v[72:73], 0
	v_mov_b64_e32 v[74:75], 0
	v_mov_b64_e32 v[76:77], 0
	v_mov_b64_e32 v[78:79], 0
	v_mov_b64_e32 v[80:81], 0
	v_mov_b64_e32 v[82:83], 0
	v_mov_b64_e32 v[84:85], 0
	v_mov_b64_e32 v[86:87], 0
	v_mov_b64_e32 v[88:89], 0
	v_mov_b64_e32 v[90:91], 0
	v_mov_b64_e32 v[92:93], 0
	v_mov_b64_e32 v[94:95], 0
	v_mov_b64_e32 v[96:97], 0
	v_mov_b64_e32 v[98:99], 0
	v_mov_b64_e32 v[100:101], 0
	v_mov_b64_e32 v[102:103], 0
	v_mov_b64_e32 v[104:105], 0
	v_mov_b64_e32 v[106:107], 0
	v_mov_b64_e32 v[108:109], 0
	v_mov_b64_e32 v[110:111], 0
	v_mov_b64_e32 v[112:113], 0
	v_mov_b64_e32 v[114:115], 0
	v_mov_b64_e32 v[116:117], 0
	v_mov_b64_e32 v[118:119], 0
	v_mov_b64_e32 v[120:121], 0
	v_mov_b64_e32 v[122:123], 0
	v_mov_b64_e32 v[124:125], 0
	v_mov_b64_e32 v[126:127], 0
	v_mov_b64_e32 v[128:129], 0
	v_add_u32_e32 v160, 0x80, v178
	v_add_u32_e32 v162, 0x80, v174
	v_add_u32_e32 v164, 0x80, v180
	v_add_u32_e32 v170, 0x80, v176
	v_add_u32_e32 v161, 0x10000, v214
	s_branch .LBB0_199

; #define PG8_STAGE(bufoff, gbase, voff) do { _Pragma("unroll") for (int _i = 0; _i < 2; ++_i) \
;         __builtin_amdgcn_global_load_lds((const unsigned*)((const char*)(gbase) + (voff)[_i]), (LAS unsigned*)(lds + (bufoff) + ldsw + _i * 8192), 16, 0, 0); } while (0)
; #define PG8_WAIT_V(n) asm volatile("s_waitcnt vmcnt(" #n ")" ::: "memory")
; #define PG8_BAR __builtin_amdgcn_s_barrier()
; template <class Epi>
; __device__ __forceinline__ void gemm_phase(LAS unsigned char* lds, const Gemm g0, const StaticOrder& S, const Epi& E) {
;     ...
;     f32x4 acc[2][2][4][2];
; #pragma unroll
;     for (int a = 0; a < 2; ++a)
; #pragma unroll
;         for (int b = 0; b < 2; ++b)
; #pragma unroll
;             for (int m = 0; m < 4; ++m)
; #pragma unroll
;                 for (int n = 0; n < 2; ++n) acc[a][b][m][n] = (f32x4){0.f, 0.f, 0.f, 0.f};
;     f16x8 At[4][2], B0[2][2], B1[2][2];
;     const char* cA = (const char*)g.A + (size_t)cur.pm * tstep; const char* cB = (const char*)g.Bt + (size_t)cur.pn * tstep;
;     PG8_STAGE(PG8_SB(0, 0), cB, voffB); PG8_STAGE(PG8_SA(0, 0), cA, voffA); PG8_STAGE(PG8_SB(0, 1), cB + hstep, voffB); PG8_STAGE(PG8_SA(0, 1), cA + hstep, voffA);
;     if (wr == 1) PG8_BAR;
;     PG8_WAIT_V(4); PG8_BAR;
;     PG8_STAGE(PG8_SB(1, 0), cB + kstep, voffB); PG8_STAGE(PG8_SA(1, 0), cA + kstep, voffA); PG8_STAGE(PG8_SB(1, 1), cB + hstep + kstep, voffB);
;     PG8_WAIT_V(6); PG8_BAR;
;     for (;;) {
;         const bool has_next = S.next(ui + 1, nxt);
;         const char* nA = has_next ? (const char*)g.A + (size_t)nxt.pm * tstep : cA; const char* nB = has_next ? (const char*)g.Bt + (size_t)nxt.pn * tstep : cB;
.LBB0_301:
	s_ashr_i32 s15, s14, 31
	v_cmp_lt_i64_e32 vcc, s[20:21], v[248:249]
	s_lshl_b64 s[20:21], s[14:15], 20
	s_add_u32 s20, s8, s20
	s_addc_u32 s21, s9, s21
	s_and_b64 s[22:23], vcc, exec
	s_cselect_b32 s15, s21, s35
	s_cselect_b32 s52, s20, s34
	s_ashr_i32 s13, s12, 31
	s_lshl_b64 s[22:23], s[12:13], 20
	s_add_u32 s26, s10, s22
	s_addc_u32 s27, s11, s23
	s_and_b64 s[22:23], vcc, exec
	s_cselect_b32 s13, s27, s7
	s_cselect_b32 s24, s26, s6
	s_add_u32 s25, s6, 0x100
	s_addc_u32 s53, s7, 0
	s_add_u32 s6, s34, 0x80080
	v_mov_b32_e32 v2, 0
	s_addc_u32 s7, s35, 0
	s_mov_b32 s58, -2
	v_mov_b32_e32 v3, v2
	v_mov_b64_e32 v[4:5], 0
	v_mov_b64_e32 v[6:7], 0
	v_mov_b64_e32 v[8:9], 0
	v_mov_b64_e32 v[10:11], 0
	v_mov_b64_e32 v[12:13], 0
	v_mov_b64_e32 v[14:15], 0
	v_mov_b64_e32 v[16:17], 0
	v_mov_b64_e32 v[18:19], 0
	v_mov_b64_e32 v[20:21], 0
	v_mov_b64_e32 v[22:23], 0
	v_mov_b64_e32 v[24:25], 0
	v_mov_b64_e32 v[26:27], 0
	v_mov_b64_e32 v[28:29], 0
	v_mov_b64_e32 v[30:31], 0
	v_mov_b64_e32 v[32:33], 0
	v_mov_b64_e32 v[34:35], 0
	v_mov_b64_e32 v[36:37], 0
	v_mov_b64_e32 v[38:39], 0
	v_mov_b64_e32 v[40:41], 0
	v_mov_b64_e32 v[42:43], 0
	v_mov_b64_e32 v[44:45], 0
	v_mov_b64_e32 v[46:47], 0
	v_mov_b64_e32 v[48:49], 0
	v_mov_b64_e32 v[50:51], 0
	v_mov_b64_e32 v[52:53], 0
	v_mov_b64_e32 v[54:55], 0
	v_mov_b64_e32 v[56:57], 0
	v_mov_b64_e32 v[58:59], 0
	v_mov_b64_e32 v[60:61], 0
	v_mov_b64_e32 v[62:63], 0
	v_mov_b64_e32 v[64:65], 0
	v_mov_b64_e32 v[66:67], 0
	v_mov_b64_e32 v[68:69], 0
	v_mov_b64_e32 v[70:71], 0
	v_mov_b64_e32 v[72:73], 0
	v_mov_b64_e32 v[74:75], 0
	v_mov_b64_e32 v[76:77], 0
	v_mov_b64_e32 v[78:79], 0
	v_mov_b64_e32 v[80:81], 0
	v_mov_b64_e32 v[82:83], 0
	v_mov_b64_e32 v[84:85], 0
	v_mov_b64_e32 v[86:87], 0
	v_mov_b64_e32 v[88:89], 0
	v_mov_b64_e32 v[90:91], 0
	v_mov_b64_e32 v[92:93], 0
	v_mov_b64_e32 v[94:95], 0
	v_mov_b64_e32 v[96:97], 0
	v_mov_b64_e32 v[98:99], 0
	v_mov_b64_e32 v[100:101], 0
	v_mov_b64_e32 v[102:103], 0
	v_mov_b64_e32 v[104:105], 0
	v_mov_b64_e32 v[106:107], 0
	v_mov_b64_e32 v[108:109], 0
	v_mov_b64_e32 v[110:111], 0
	v_mov_b64_e32 v[112:113], 0
	v_mov_b64_e32 v[114:115], 0
	v_mov_b64_e32 v[116:117], 0
	v_mov_b64_e32 v[118:119], 0
	v_mov_b64_e32 v[120:121], 0
	v_mov_b64_e32 v[122:123], 0
	v_mov_b64_e32 v[124:125], 0
	v_mov_b64_e32 v[126:127], 0
	v_mov_b64_e32 v[128:129], 0
	v_add_u32_e32 v146, 0x80, v134
	v_add_u32_e32 v160, 0x80, v130
	v_add_u32_e32 v162, 0x80, v136
	v_add_u32_e32 v164, 0x80, v132
	v_add_u32_e32 v161, 0x10000, v148

; #define PG8_STAGE(bufoff, gbase, voff) do { _Pragma("unroll") for (int _i = 0; _i < 2; ++_i) \
;         __builtin_amdgcn_global_load_lds((const unsigned*)((const char*)(gbase) + (voff)[_i]), (LAS unsigned*)(lds + (bufoff) + ldsw + _i * 8192), 16, 0, 0); } while (0)
; #define PG8_WAIT_V(n) asm volatile("s_waitcnt vmcnt(" #n ")" ::: "memory")
; #define PG8_BAR __builtin_amdgcn_s_barrier()
; template <class Epi>
; __device__ __forceinline__ void gemm_phase(LAS unsigned char* lds, const Gemm g0, const StaticOrder& S, const Epi& E) {
;     ...
;     f32x4 acc[2][2][4][2];
; #pragma unroll
;     for (int a = 0; a < 2; ++a)
; #pragma unroll
;         for (int b = 0; b < 2; ++b)
; #pragma unroll
;             for (int m = 0; m < 4; ++m)
; #pragma unroll
;                 for (int n = 0; n < 2; ++n) acc[a][b][m][n] = (f32x4){0.f, 0.f, 0.f, 0.f};
;     f16x8 At[4][2], B0[2][2], B1[2][2];
;     const char* cA = (const char*)g.A + (size_t)cur.pm * tstep; const char* cB = (const char*)g.Bt + (size_t)cur.pn * tstep;
;     PG8_STAGE(PG8_SB(0, 0), cB, voffB); PG8_STAGE(PG8_SA(0, 0), cA, voffA); PG8_STAGE(PG8_SB(0, 1), cB + hstep, voffB); PG8_STAGE(PG8_SA(0, 1), cA + hstep, voffA);
;     if (wr == 1) PG8_BAR;
;     PG8_WAIT_V(4); PG8_BAR;
;     PG8_STAGE(PG8_SB(1, 0), cB + kstep, voffB); PG8_STAGE(PG8_SA(1, 0), cA + kstep, voffA); PG8_STAGE(PG8_SB(1, 1), cB + hstep + kstep, voffB);
;     PG8_WAIT_V(6); PG8_BAR;
;     for (;;) {
;         const bool has_next = S.next(ui + 1, nxt);
;         const char* nA = has_next ? (const char*)g.A + (size_t)nxt.pm * tstep : cA; const char* nB = has_next ? (const char*)g.Bt + (size_t)nxt.pn * tstep : cB;
.LBB0_511:
	s_ashr_i32 s15, s14, 31
	s_lshl_b64 s[22:23], s[14:15], 20
	v_cmp_lt_i64_e32 vcc, s[36:37], v[168:169]
	s_add_u32 s36, s92, s22
	s_addc_u32 s37, s93, s23
	s_and_b64 s[22:23], vcc, exec
	s_cselect_b32 s15, s37, s49
	s_cselect_b32 s24, s36, s48
	s_ashr_i32 s53, s52, 31
	s_lshl_b64 s[22:23], s[52:53], 20
	s_add_u32 s38, s96, s22
	s_addc_u32 s39, s97, s23
	s_and_b64 s[22:23], vcc, exec
	s_cselect_b32 s25, s39, s13
	s_cselect_b32 s53, s38, s12
	s_add_u32 vcc_lo, s12, 0x100
	s_addc_u32 vcc_hi, s13, 0
	s_add_u32 s12, s48, 0x80080
	v_mov_b32_e32 v2, 0
	s_addc_u32 s13, s49, 0
	s_mov_b32 s22, -2
	v_mov_b32_e32 v3, v2
	v_mov_b64_e32 v[4:5], 0
	v_mov_b64_e32 v[6:7], 0
	v_mov_b64_e32 v[8:9], 0
	v_mov_b64_e32 v[10:11], 0
	v_mov_b64_e32 v[12:13], 0
	v_mov_b64_e32 v[14:15], 0
	v_mov_b64_e32 v[16:17], 0
	v_mov_b64_e32 v[18:19], 0
	v_mov_b64_e32 v[20:21], 0
	v_mov_b64_e32 v[22:23], 0
	v_mov_b64_e32 v[24:25], 0
	v_mov_b64_e32 v[26:27], 0
	v_mov_b64_e32 v[28:29], 0
	v_mov_b64_e32 v[30:31], 0
	v_mov_b64_e32 v[32:33], 0
	v_mov_b64_e32 v[34:35], 0
	v_mov_b64_e32 v[36:37], 0
	v_mov_b64_e32 v[38:39], 0
	v_mov_b64_e32 v[40:41], 0
	v_mov_b64_e32 v[42:43], 0
	v_mov_b64_e32 v[44:45], 0
	v_mov_b64_e32 v[46:47], 0
	v_mov_b64_e32 v[48:49], 0
	v_mov_b64_e32 v[50:51], 0
	v_mov_b64_e32 v[52:53], 0
	v_mov_b64_e32 v[54:55], 0
	v_mov_b64_e32 v[56:57], 0
	v_mov_b64_e32 v[58:59], 0
	v_mov_b64_e32 v[60:61], 0
	v_mov_b64_e32 v[62:63], 0
	v_mov_b64_e32 v[64:65], 0
	v_mov_b64_e32 v[66:67], 0
	v_mov_b64_e32 v[68:69], 0
	v_mov_b64_e32 v[70:71], 0
	v_mov_b64_e32 v[72:73], 0
	v_mov_b64_e32 v[82:83], 0
	v_mov_b64_e32 v[84:85], 0
	v_mov_b64_e32 v[86:87], 0
	v_mov_b64_e32 v[88:89], 0
	v_mov_b64_e32 v[98:99], 0
	s_waitcnt vmcnt(0)
	v_mov_b32_e32 v100, v2
	v_mov_b32_e32 v101, v2
	v_mov_b32_e32 v102, v2
	v_mov_b32_e32 v103, v2
	v_mov_b32_e32 v104, v2
	v_mov_b32_e32 v105, v2
	v_mov_b32_e32 v114, v2
	v_mov_b32_e32 v115, v2
	v_mov_b32_e32 v116, v2
	v_mov_b32_e32 v117, v2
	v_mov_b32_e32 v118, v2
	v_mov_b32_e32 v119, v2
	v_mov_b32_e32 v120, v2
	v_mov_b32_e32 v121, v2
	v_mov_b32_e32 v74, v2
	v_mov_b32_e32 v75, v2
	v_mov_b32_e32 v76, v2
	v_mov_b32_e32 v77, v2
	v_mov_b32_e32 v78, v2
	v_mov_b32_e32 v79, v2
	v_mov_b32_e32 v80, v2
	v_mov_b32_e32 v81, v2
	v_mov_b32_e32 v90, v2
	v_mov_b32_e32 v91, v2
	v_mov_b32_e32 v92, v2
	v_mov_b32_e32 v93, v2
	v_mov_b32_e32 v94, v2
	v_mov_b32_e32 v95, v2
	v_mov_b32_e32 v96, v2
	v_mov_b32_e32 v97, v2
	v_mov_b32_e32 v106, v2
	v_mov_b32_e32 v107, v2
	v_mov_b32_e32 v108, v2
	v_mov_b32_e32 v109, v2
	v_mov_b32_e32 v110, v2
	v_mov_b32_e32 v111, v2
	v_mov_b32_e32 v112, v2
	v_mov_b32_e32 v113, v2
	v_mov_b32_e32 v130, v2
	v_mov_b32_e32 v131, v2
	v_mov_b32_e32 v132, v2
	v_mov_b32_e32 v133, v2
	v_mov_b32_e32 v134, v2
	v_mov_b32_e32 v135, v2
	v_mov_b32_e32 v136, v2
	v_mov_b32_e32 v137, v2
	v_add_u32_e32 v164, 0x80, v174
	v_add_u32_e32 v165, 0x10000, v205

; #define LAS __attribute__((address_space(3)))
; #define PG8_STAGE(bufoff, gbase, voff) do { _Pragma("unroll") for (int _i = 0; _i < 2; ++_i) \
;         __builtin_amdgcn_global_load_lds((const unsigned*)((const char*)(gbase) + (voff)[_i]), (LAS unsigned*)(lds + (bufoff) + ldsw + _i * 8192), 16, 0, 0); } while (0)
; #define PG8_WAIT_V(n) asm volatile("s_waitcnt vmcnt(" #n ")" ::: "memory")
; #define PG8_BAR __builtin_amdgcn_s_barrier()
; __device__ __forceinline__ void lnfold_prefetch(LAS float* vl, const float* stats, const float* gW, const float* bW, const Unit& u, int wr, int wc, int lane) {
;     LAS float* slot = vl + (wr * 4 + wc) * 512;
;     const int rowb = u.pm * BM + wr * 64 + (lane >> 5) * HALF + (lane & 31) * 2;
;     const int col = u.pn * BM + wc * 32 + (lane < 32 ? lane : 96 + lane);
;     __builtin_amdgcn_global_load_lds((const unsigned*)(stats + 2 * (size_t)rowb), (LAS unsigned*)slot, 16, 0, 0);
;     __builtin_amdgcn_global_load_lds((const unsigned*)(gW + col), (LAS unsigned*)(slot + 256), 4, 0, 0);
;     __builtin_amdgcn_global_load_lds((const unsigned*)(bW + col), (LAS unsigned*)(slot + 320), 4, 0, 0);
; template <class Epi>
; __device__ __forceinline__ void gemm_phase(LAS unsigned char* lds, const Gemm g0, const StaticOrder& S, const Epi& E) {
;     ...
;     f32x4 acc[2][2][4][2];
; #pragma unroll
;     for (int a = 0; a < 2; ++a)
; #pragma unroll
;         for (int b = 0; b < 2; ++b)
; #pragma unroll
;             for (int m = 0; m < 4; ++m)
; #pragma unroll
;                 for (int n = 0; n < 2; ++n) acc[a][b][m][n] = (f32x4){0.f, 0.f, 0.f, 0.f};
;     f16x8 At[4][2], B0[2][2], B1[2][2];
;     const char* cA = (const char*)g.A + (size_t)cur.pm * tstep; const char* cB = (const char*)g.Bt + (size_t)cur.pn * tstep;
;     PG8_STAGE(PG8_SB(0, 0), cB, voffB); PG8_STAGE(PG8_SA(0, 0), cA, voffA); PG8_STAGE(PG8_SB(0, 1), cB + hstep, voffB); PG8_STAGE(PG8_SA(0, 1), cA + hstep, voffA);
;     if (wr == 1) PG8_BAR;
;     PG8_WAIT_V(4); PG8_BAR;
;     PG8_STAGE(PG8_SB(1, 0), cB + kstep, voffB); PG8_STAGE(PG8_SA(1, 0), cA + kstep, voffA); PG8_STAGE(PG8_SB(1, 1), cB + hstep + kstep, voffB);
;     PG8_WAIT_V(6); PG8_BAR;
;     for (;;) {
;         const bool has_next = S.next(ui + 1, nxt);
;         const char* nA = has_next ? (const char*)g.A + (size_t)nxt.pm * tstep : cA; const char* nB = has_next ? (const char*)g.Bt + (size_t)nxt.pn * tstep : cB;
.LBB0_619:
	s_ashr_i32 s37, s36, 31
	s_lshl_b64 s[24:25], s[36:37], 20
	v_cmp_lt_i64_e32 vcc, s[38:39], v[230:231]
	s_add_u32 s38, s8, s24
	s_addc_u32 s39, s9, s25
	s_and_b64 s[24:25], vcc, exec
	s_cselect_b32 s37, s39, s53
	s_cselect_b32 s74, s38, s52
	s_ashr_i32 s35, s34, 31
	s_lshl_b64 s[24:25], s[34:35], 20
	s_add_u32 s48, s10, s24
	s_addc_u32 s49, s11, s25
	s_and_b64 s[24:25], vcc, exec
	s_cselect_b32 s35, s49, s51
	s_cselect_b32 s75, s48, s50
	s_lshl_b32 s80, s22, 8
	v_add_u32_e32 v2, s80, v193
	v_lshl_add_u32 v4, s71, 8, v201
	s_add_u32 s24, s50, 0x100
	v_ashrrev_i32_e32 v3, 31, v2
	v_ashrrev_i32_e32 v5, 31, v4
	s_addc_u32 s25, s51, 0
	v_lshlrev_b64 v[4:5], 2, v[4:5]
	v_lshl_add_u64 v[58:59], v[2:3], 3, s[14:15]
	s_add_u32 s50, s52, 0x80080
	v_mov_b32_e32 v2, 0
	v_lshl_add_u64 v[54:55], s[26:27], 0, v[4:5]
	v_lshl_add_u64 v[56:57], s[20:21], 0, v[4:5]
	s_addc_u32 s51, s53, 0
	s_mov_b32 s81, -2
	v_mov_b32_e32 v3, v2
	v_mov_b64_e32 v[4:5], 0
	v_mov_b64_e32 v[6:7], 0
	v_mov_b64_e32 v[8:9], 0
	v_mov_b64_e32 v[10:11], 0
	v_mov_b64_e32 v[12:13], 0
	v_mov_b64_e32 v[14:15], 0
	v_mov_b64_e32 v[16:17], 0
	v_mov_b64_e32 v[18:19], 0
	v_mov_b64_e32 v[20:21], 0
	v_mov_b64_e32 v[22:23], 0
	v_mov_b64_e32 v[24:25], 0
	v_mov_b64_e32 v[26:27], 0
	v_mov_b64_e32 v[28:29], 0
	v_mov_b64_e32 v[30:31], 0
	v_mov_b64_e32 v[32:33], 0
	v_mov_b64_e32 v[34:35], 0
	v_mov_b64_e32 v[36:37], 0
	v_mov_b64_e32 v[38:39], 0
	v_mov_b64_e32 v[40:41], 0
	v_mov_b64_e32 v[42:43], 0
	v_mov_b64_e32 v[44:45], 0
	v_mov_b64_e32 v[46:47], 0
	v_mov_b64_e32 v[48:49], 0
	v_mov_b64_e32 v[50:51], 0
	v_mov_b64_e32 v[52:53], 0
	v_mov_b64_e32 v[70:71], 0
	v_mov_b64_e32 v[72:73], 0
	v_mov_b64_e32 v[74:75], 0
	v_mov_b64_e32 v[76:77], 0
	v_mov_b64_e32 v[94:95], 0
	v_mov_b64_e32 v[96:97], 0
	v_mov_b64_e32 v[98:99], 0
	v_mov_b64_e32 v[100:101], 0
	v_mov_b64_e32 v[102:103], 0
	v_mov_b64_e32 v[104:105], 0
	v_mov_b64_e32 v[106:107], 0
	v_mov_b64_e32 v[108:109], 0
	v_mov_b64_e32 v[110:111], 0
	v_mov_b64_e32 v[112:113], 0
	v_mov_b64_e32 v[114:115], 0
	v_mov_b64_e32 v[116:117], 0
	v_mov_b64_e32 v[118:119], 0
	v_mov_b64_e32 v[120:121], 0
	v_mov_b64_e32 v[122:123], 0
	v_mov_b64_e32 v[124:125], 0
	v_mov_b64_e32 v[126:127], 0
	v_mov_b64_e32 v[128:129], 0
	v_mov_b64_e32 v[130:131], 0
	v_mov_b64_e32 v[132:133], 0
	v_mov_b64_e32 v[134:135], 0
	v_mov_b64_e32 v[136:137], 0
	v_mov_b64_e32 v[138:139], 0
	v_mov_b64_e32 v[140:141], 0
	v_mov_b64_e32 v[142:143], 0
	v_mov_b64_e32 v[144:145], 0
	v_mov_b64_e32 v[146:147], 0
	v_mov_b64_e32 v[148:149], 0
	v_mov_b64_e32 v[150:151], 0
	v_mov_b64_e32 v[152:153], 0
	v_mov_b64_e32 v[154:155], 0
	v_mov_b64_e32 v[156:157], 0
	v_mov_b64_e32 v[158:159], 0
	v_mov_b64_e32 v[160:161], 0
	v_add_u32_e32 v186, 0x80, v178
	v_add_u32_e32 v190, 0x80, v174
	v_add_u32_e32 v198, 0x80, v180
	v_add_u32_e32 v202, 0x80, v176
	v_add_u32_e32 v187, 0x10000, v189
	s_branch .LBB0_621

; #define PG8_STAGE(bufoff, gbase, voff) do { _Pragma("unroll") for (int _i = 0; _i < 2; ++_i) \
;         __builtin_amdgcn_global_load_lds((const unsigned*)((const char*)(gbase) + (voff)[_i]), (LAS unsigned*)(lds + (bufoff) + ldsw + _i * 8192), 16, 0, 0); } while (0)
; #define PG8_WAIT_V(n) asm volatile("s_waitcnt vmcnt(" #n ")" ::: "memory")
; #define PG8_BAR __builtin_amdgcn_s_barrier()
; template <class Epi>
; __device__ __forceinline__ void gemm_phase(LAS unsigned char* lds, const Gemm g0, const StaticOrder& S, const Epi& E) {
;     ...
;     f32x4 acc[2][2][4][2];
; #pragma unroll
;     for (int a = 0; a < 2; ++a)
; #pragma unroll
;         for (int b = 0; b < 2; ++b)
; #pragma unroll
;             for (int m = 0; m < 4; ++m)
; #pragma unroll
;                 for (int n = 0; n < 2; ++n) acc[a][b][m][n] = (f32x4){0.f, 0.f, 0.f, 0.f};
;     f16x8 At[4][2], B0[2][2], B1[2][2];
;     const char* cA = (const char*)g.A + (size_t)cur.pm * tstep; const char* cB = (const char*)g.Bt + (size_t)cur.pn * tstep;
;     PG8_STAGE(PG8_SB(0, 0), cB, voffB); PG8_STAGE(PG8_SA(0, 0), cA, voffA); PG8_STAGE(PG8_SB(0, 1), cB + hstep, voffB); PG8_STAGE(PG8_SA(0, 1), cA + hstep, voffA);
;     if (wr == 1) PG8_BAR;
;     PG8_WAIT_V(4); PG8_BAR;
;     PG8_STAGE(PG8_SB(1, 0), cB + kstep, voffB); PG8_STAGE(PG8_SA(1, 0), cA + kstep, voffA); PG8_STAGE(PG8_SB(1, 1), cB + hstep + kstep, voffB);
;     PG8_WAIT_V(6); PG8_BAR;
;     for (;;) {
;         const bool has_next = S.next(ui + 1, nxt);
;         const char* nA = has_next ? (const char*)g.A + (size_t)nxt.pm * tstep : cA; const char* nB = has_next ? (const char*)g.Bt + (size_t)nxt.pn * tstep : cB;
.LBB0_671:
	s_add_u32 s24, s62, 0x100
	v_mov_b32_e32 v2, 0
	s_addc_u32 s25, s63, 0
	s_mov_b32 s22, -2
	s_waitcnt lgkmcnt(0)
	v_mov_b32_e32 v3, v2
	v_mov_b64_e32 v[4:5], 0
	v_mov_b64_e32 v[6:7], 0
	v_mov_b64_e32 v[8:9], 0
	v_mov_b64_e32 v[10:11], 0
	v_mov_b64_e32 v[12:13], 0
	v_mov_b64_e32 v[14:15], 0
	v_mov_b64_e32 v[16:17], 0
	v_mov_b64_e32 v[18:19], 0
	v_mov_b64_e32 v[20:21], 0
	v_mov_b64_e32 v[22:23], 0
	v_mov_b64_e32 v[24:25], 0
	v_mov_b64_e32 v[26:27], 0
	v_mov_b64_e32 v[28:29], 0
	v_mov_b64_e32 v[30:31], 0
	v_mov_b64_e32 v[32:33], 0
	v_mov_b64_e32 v[34:35], 0
	v_mov_b64_e32 v[36:37], 0
	v_mov_b64_e32 v[38:39], 0
	v_mov_b64_e32 v[40:41], 0
	v_mov_b64_e32 v[42:43], 0
	v_mov_b64_e32 v[44:45], 0
	v_mov_b64_e32 v[46:47], 0
	v_mov_b64_e32 v[48:49], 0
	v_mov_b64_e32 v[50:51], 0
	v_mov_b64_e32 v[52:53], 0
	v_mov_b64_e32 v[54:55], 0
	v_mov_b64_e32 v[56:57], 0
	v_mov_b64_e32 v[58:59], 0
	v_mov_b64_e32 v[60:61], 0
	v_mov_b64_e32 v[62:63], 0
	v_mov_b64_e32 v[64:65], 0
	v_mov_b64_e32 v[66:67], 0
	v_mov_b64_e32 v[68:69], 0
	v_mov_b64_e32 v[70:71], 0
	v_mov_b64_e32 v[72:73], 0
	v_mov_b64_e32 v[74:75], 0
	v_mov_b64_e32 v[76:77], 0
	v_mov_b64_e32 v[78:79], 0
	v_mov_b64_e32 v[80:81], 0
	v_mov_b64_e32 v[82:83], 0
	v_mov_b64_e32 v[84:85], 0
	v_mov_b64_e32 v[86:87], 0
	v_mov_b64_e32 v[88:89], 0
	v_mov_b64_e32 v[90:91], 0
	v_mov_b64_e32 v[92:93], 0
	v_mov_b64_e32 v[94:95], 0
	v_mov_b64_e32 v[96:97], 0
	v_mov_b64_e32 v[98:99], 0
	v_mov_b64_e32 v[100:101], 0
	v_mov_b64_e32 v[102:103], 0
	v_mov_b64_e32 v[104:105], 0
	v_mov_b64_e32 v[106:107], 0
	v_mov_b64_e32 v[108:109], 0
	v_mov_b64_e32 v[110:111], 0
	v_mov_b64_e32 v[112:113], 0
	v_mov_b64_e32 v[114:115], 0
	v_mov_b64_e32 v[116:117], 0
	v_mov_b64_e32 v[118:119], 0
	v_mov_b64_e32 v[120:121], 0
	v_mov_b64_e32 v[122:123], 0
	v_mov_b64_e32 v[124:125], 0
	v_mov_b64_e32 v[126:127], 0
	v_mov_b64_e32 v[128:129], 0
	v_add_u32_e32 v200, 0x80, v174
	v_add_u32_e32 v218, 0x80, v158
	v_add_u32_e32 v226, 0x80, v176
	v_add_u32_e32 v228, 0x80, v160
	v_add_u32_e32 v201, 0x10000, v203
